# P0b x-row loads: lanes 0-31 / 32-63 fetch the first / second KiB of each 2 KiB span (full lines per instruction), v_permlane32_swap restores the register contents
# speedup vs baseline: 1.0113x; 1.0035x over previous
; #define P0B_LOAD(dst_, r0_) do { _Pragma("unroll") for (int rr = 0; rr < 2; ++rr) { const int row = min((r0_) + rr * NGW, NTOK - 1); \
;             const float* xr = row < NP ? P.xp + (size_t)row * DM : P.xs + (size_t)(row - NP) * DM; \
;             _Pragma("unroll") for (int j = 0; j < 4; ++j) dst_[rr][j] = *(const f32x4*)(xr + 8 * lane + 512 * (j >> 1) + 4 * (j & 1)); } } while (0)
; __device__ __forceinline__ void phase0b(const Params& P, int lane, int wave, int bid, int G) {
;     const float* mod = (const float*)(P.ws + OFF_MOD); bf16_t* H = (bf16_t*)(P.ws + OFF_H);
;     const int gw = bid * 8 + wave, NGW = G * 8;
;     f32x4 v[2][4], vn[2][4];
;     ...
;     P0B_LOAD(v, gw);
;     for (int row0 = gw; row0 < NTOK; row0 += 2 * NGW) {
;         P0B_LOAD(vn, row0 + 2 * NGW);
;     ...
; #pragma unroll
;         for (int rr = 0; rr < 2; ++rr)
; #pragma unroll
;             for (int j = 0; j < 4; ++j) v[rr][j] = vn[rr][j];
.LBB0_90:
	s_cmp_lt_i32 s28, 2
	s_cselect_b64 s[0:1], -1, 0
	s_and_b64 s[4:5], s[0:1], s[6:7]
	s_andn2_b64 vcc, exec, s[4:5]
	s_cbranch_vccnz .LBB0_96
	s_lshl_b32 s16, s2, 3
	s_add_i32 s6, s97, s16
	s_cmp_gt_i32 s6, 0x13fff
	s_cbranch_scc1 .LBB0_96
	s_add_u32 s17, s22, 0x10000
	s_addc_u32 s18, s23, 0
	s_lshl_b32 s5, s3, 3
	s_add_i32 s5, s5, s6
	s_min_i32 s7, s5, 0x13fff
	s_lshl_b32 s4, s3, 4
	s_ashr_i32 s10, s7, 31
	s_add_i32 s12, s7, 0xffff0000
	s_cmp_lt_i32 s5, 0x10000
	s_cselect_b32 s11, s10, 0
	s_cselect_b32 s10, s7, s12
	s_cselect_b32 s5, s37, s39
	s_cselect_b32 s13, s36, s38
	s_lshl_b64 s[10:11], s[10:11], 12
	s_add_u32 s10, s13, s10
	s_addc_u32 s11, s5, s11
	s_ashr_i32 s7, s6, 31
	s_add_i32 s5, s6, 0xffff0000
	s_cmp_lt_i32 s6, 0x10000
	s_cselect_b32 s13, s7, 0
	s_cselect_b32 s12, s6, s5
	s_cselect_b32 s14, s37, s39
	s_cselect_b32 s15, s36, s38
	s_lshl_b64 s[12:13], s[12:13], 12
	s_add_u32 s12, s15, s12
	v_lshlrev_b32_e32 v10, 5, v180
	v_and_b32_e32 v120, 31, v180
	v_lshlrev_b32_e32 v120, 5, v120
	v_lshrrev_b32_e32 v121, 5, v180
	v_lshl_or_b32 v120, v121, 4, v120
	s_addc_u32 s13, s14, s13
	global_load_dwordx4 v[50:53], v120, s[12:13] offset:3072
	global_load_dwordx4 v[54:57], v120, s[12:13] offset:2048
	global_load_dwordx4 v[58:61], v120, s[12:13] offset:1024
	global_load_dwordx4 v[62:65], v120, s[12:13]
	global_load_dwordx4 v[2:5], v120, s[10:11] offset:3072
	global_load_dwordx4 v[6:9], v120, s[10:11] offset:2048
	global_load_dwordx4 v[42:45], v120, s[10:11] offset:1024
	global_load_dwordx4 v[46:49], v120, s[10:11]
	s_lshl_b64 s[6:7], s[6:7], 11
	v_mov_b32_e32 v11, 0
	s_add_u32 s6, s22, s6
	v_lshlrev_b32_e32 v66, 3, v180
	v_lshl_add_u64 v[68:69], s[44:45], 0, v[10:11]
	v_lshlrev_b32_e32 v10, 4, v180
	s_addc_u32 s7, s23, s7
	s_ashr_i32 s5, s4, 31
	v_or_b32_e32 v12, 0x200, v66
	v_lshl_add_u64 v[14:15], s[22:23], 0, v[10:11]
	s_mov_b64 s[10:11], 0x2000000
	v_lshl_add_u64 v[10:11], s[6:7], 0, v[10:11]
	s_lshl_b64 s[6:7], s[4:5], 11
	s_add_i32 s5, s2, s3
	s_mul_i32 s19, s3, 24
	v_mbcnt_lo_u32_b32 v1, -1, 0
	v_lshl_add_u64 v[70:71], v[14:15], 0, s[10:11]
	v_lshl_add_u64 v[72:73], v[10:11], 0, s[10:11]
	s_lshl_b32 s5, s5, 3
	s_add_i32 s19, s19, s16
	s_add_i32 s20, s4, s16
	v_mbcnt_hi_u32_b32 v1, -1, v1
	v_mov_b32_e32 v67, 0x358637bd
	s_mov_b32 s21, 0x800000
	v_lshlrev_b32_e32 v74, 2, v12
	s_mov_b32 s24, s97
	s_waitcnt vmcnt(0)
	s_nop 1
	v_permlane32_swap_b32_e32 v62, v58
	v_permlane32_swap_b32_e32 v63, v59
	v_permlane32_swap_b32_e32 v64, v60
	v_permlane32_swap_b32_e32 v65, v61
	v_permlane32_swap_b32_e32 v54, v50
	v_permlane32_swap_b32_e32 v55, v51
	v_permlane32_swap_b32_e32 v56, v52
	v_permlane32_swap_b32_e32 v57, v53
	v_permlane32_swap_b32_e32 v46, v42
	v_permlane32_swap_b32_e32 v47, v43
	v_permlane32_swap_b32_e32 v48, v44
	v_permlane32_swap_b32_e32 v49, v45
	v_permlane32_swap_b32_e32 v6, v2
	v_permlane32_swap_b32_e32 v7, v3
	v_permlane32_swap_b32_e32 v8, v4
	v_permlane32_swap_b32_e32 v9, v5
	s_branch .LBB0_94
.LBB0_93:
	s_add_i32 s24, s24, s4
	s_add_i32 s10, s16, s24
	v_mov_b64_e32 v[64:65], v[24:25]
	v_mov_b64_e32 v[60:61], v[16:17]
	v_mov_b64_e32 v[56:57], v[20:21]
	v_mov_b64_e32 v[52:53], v[12:13]
	v_mov_b64_e32 v[48:49], v[40:41]
	v_mov_b64_e32 v[44:45], v[32:33]
	v_mov_b64_e32 v[6:7], v[34:35]
	v_mov_b64_e32 v[2:3], v[26:27]
	v_lshl_add_u64 v[72:73], v[72:73], 0, s[6:7]
	s_cmp_lt_i32 s10, 0x14000
	v_mov_b64_e32 v[62:63], v[22:23]
	v_mov_b64_e32 v[58:59], v[14:15]
	v_mov_b64_e32 v[54:55], v[18:19]
	v_mov_b64_e32 v[50:51], v[10:11]
	v_mov_b64_e32 v[46:47], v[38:39]
	v_mov_b64_e32 v[42:43], v[30:31]
	v_mov_b64_e32 v[8:9], v[36:37]
	v_mov_b64_e32 v[4:5], v[28:29]
	s_nop 1
	v_permlane32_swap_b32_e32 v62, v58
	v_permlane32_swap_b32_e32 v63, v59
	v_permlane32_swap_b32_e32 v64, v60
	v_permlane32_swap_b32_e32 v65, v61
	v_permlane32_swap_b32_e32 v54, v50
	v_permlane32_swap_b32_e32 v55, v51
	v_permlane32_swap_b32_e32 v56, v52
	v_permlane32_swap_b32_e32 v57, v53
	v_permlane32_swap_b32_e32 v46, v42
	v_permlane32_swap_b32_e32 v47, v43
	v_permlane32_swap_b32_e32 v48, v44
	v_permlane32_swap_b32_e32 v49, v45
	v_permlane32_swap_b32_e32 v6, v2
	v_permlane32_swap_b32_e32 v7, v3
	v_permlane32_swap_b32_e32 v8, v4
	v_permlane32_swap_b32_e32 v9, v5
	s_cbranch_scc0 .LBB0_96
; #define P0B_LOAD(dst_, r0_) do { _Pragma("unroll") for (int rr = 0; rr < 2; ++rr) { const int row = min((r0_) + rr * NGW, NTOK - 1); \
;             const float* xr = row < NP ? P.xp + (size_t)row * DM : P.xs + (size_t)(row - NP) * DM; \
;             _Pragma("unroll") for (int j = 0; j < 4; ++j) dst_[rr][j] = *(const f32x4*)(xr + 8 * lane + 512 * (j >> 1) + 4 * (j & 1)); } } while (0)
; __device__ __forceinline__ void phase0b(const Params& P, int lane, int wave, int bid, int G) {
;     ...
;     for (int row0 = gw; row0 < NTOK; row0 += 2 * NGW) {
;         P0B_LOAD(vn, row0 + 2 * NGW);
;         asm volatile("" ::: "memory");
;         float ss[2];
; #pragma unroll
;         for (int rr = 0; rr < 2; ++rr) { float s2 = 0.f;
; #pragma unroll
;             for (int j = 0; j < 4; ++j) s2 += (v[rr][j].x * v[rr][j].x + v[rr][j].y * v[rr][j].y) + (v[rr][j].z * v[rr][j].z + v[rr][j].w * v[rr][j].w);
;             ss[rr] = s2; }
; #pragma unroll
;         for (int rr = 0; rr < 2; ++rr) { const int row = row0 + rr * NGW; if (row >= NTOK) break;
;             const int s = row < NP ? (row >> 12) : 16; const float* md = mod + s * 3072;
;             const float rstd = rsqrtf(wave_sum(ss[rr]) * (1.f / DM) + EPS);
; #pragma unroll
;             for (int jj = 0; jj < 2; ++jj) { const int c = 8 * lane + 512 * jj; f32x4 hv[2];
; #pragma unroll
;                 for (int e = 0; e < 2; ++e) { const f32x4 gn = *(const f32x4*)(P.norm_gain + c + 4 * e), sh = *(const f32x4*)(md + c + 4 * e), scv = *(const f32x4*)(md + 1024 + c + 4 * e);
.LBB0_94:
	s_add_i32 s10, s20, s24
	s_min_i32 s13, s10, 0x13fff
	s_add_i32 s12, s16, s24
	s_add_i32 s14, s13, 0xffff0000
	s_ashr_i32 s11, s13, 31
	s_cmp_lt_i32 s10, 0x10000
	s_cselect_b32 s11, s11, 0
	s_cselect_b32 s10, s13, s14
	s_cselect_b32 s13, s37, s39
	s_cselect_b32 s14, s36, s38
	s_lshl_b64 s[10:11], s[10:11], 12
	s_add_u32 s10, s14, s10
	s_addc_u32 s11, s13, s11
	v_lshlrev_b32_e32 v75, 2, v66
	global_load_dwordx4 v[14:17], v120, s[10:11] offset:1024
	global_load_dwordx4 v[22:25], v120, s[10:11]
	global_load_dwordx4 v[10:13], v120, s[10:11] offset:3072
	global_load_dwordx4 v[18:21], v120, s[10:11] offset:2048
	s_add_i32 s10, s19, s24
	s_min_i32 s13, s10, 0x13fff
	s_ashr_i32 s11, s13, 31
	s_add_i32 s14, s13, 0xffff0000
	s_cmp_lt_i32 s10, 0x10000
	s_cselect_b32 s11, s11, 0
	s_cselect_b32 s10, s13, s14
	s_cselect_b32 s13, s37, s39
	s_cselect_b32 s14, s36, s38
	s_lshl_b64 s[10:11], s[10:11], 12
	s_add_u32 s10, s14, s10
	s_addc_u32 s11, s13, s11
	s_waitcnt vmcnt(8)
	v_pk_mul_f32 v[76:77], v[64:65], v[64:65]
	v_pk_mul_f32 v[78:79], v[62:63], v[62:63]
	global_load_dwordx4 v[30:33], v120, s[10:11] offset:1024
	global_load_dwordx4 v[38:41], v120, s[10:11]
	global_load_dwordx4 v[26:29], v120, s[10:11] offset:3072
	global_load_dwordx4 v[34:37], v120, s[10:11] offset:2048
	v_pk_mov_b32 v[80:81], v[78:79], v[76:77] op_sel:[1,0]
	v_mov_b32_e32 v79, v77
	s_min_i32 s10, s12, 0x10000
	v_pk_add_f32 v[76:77], v[80:81], v[78:79]
	v_pk_mul_f32 v[78:79], v[60:61], v[60:61]
	v_pk_mul_f32 v[80:81], v[58:59], v[58:59]
	s_ashr_i32 s10, s10, 12
	v_pk_mov_b32 v[82:83], v[80:81], v[78:79] op_sel:[1,0]
	v_mov_b32_e32 v81, v79
	s_mulk_i32 s10, 0xc00
	v_pk_add_f32 v[78:79], v[82:83], v[80:81]
	s_ashr_i32 s11, s10, 31
	v_mul_f32_e32 v80, v50, v50
	v_mul_f32_e32 v81, v51, v51
	v_pk_add_f32 v[76:77], v[76:77], v[76:77] op_sel:[0,1] op_sel_hi:[1,0]
	v_pk_add_f32 v[78:79], v[78:79], v[78:79] op_sel:[0,1] op_sel_hi:[1,0]
	s_lshl_b64 s[10:11], s[10:11], 2
	v_mov_b32_e32 v77, v80
	v_mov_b32_e32 v79, v81
	s_add_u32 s10, s17, s10
	v_pk_add_f32 v[76:77], v[76:77], v[78:79]
	v_mul_f32_e32 v78, v55, v55
	v_mul_f32_e32 v80, v57, v57
	s_addc_u32 s11, s18, s11
	v_mul_f32_e32 v82, v52, v52
	v_mul_f32_e32 v83, v53, v53
	v_pk_fma_f32 v[78:79], v[54:55], v[54:55], v[78:79] op_sel_hi:[1,1,0]
	v_pk_fma_f32 v[80:81], v[56:57], v[56:57], v[80:81] op_sel_hi:[1,1,0]
	s_add_u32 s12, s10, 0x1000
	v_mov_b32_e32 v79, v82
	v_mov_b32_e32 v81, v83
	s_addc_u32 s13, s11, 0
	global_load_dwordx4 v[82:85], v[68:69], off offset:16
	global_load_dwordx4 v[86:89], v[68:69], off
	global_load_dwordx4 v[90:93], v75, s[12:13] offset:16
	global_load_dwordx4 v[94:97], v75, s[12:13]
	global_load_dwordx4 v[98:101], v75, s[10:11] offset:16
	global_load_dwordx4 v[102:105], v75, s[10:11]
	v_pk_add_f32 v[78:79], v[78:79], v[80:81]
	s_nop 0
	v_pk_add_f32 v[76:77], v[76:77], v[78:79]
	s_nop 0
	v_add_f32_e32 v77, v76, v77
	v_and_b32_e32 v76, 64, v1
	v_add_u32_e32 v81, 64, v76
	v_xor_b32_e32 v76, 1, v1
	v_cmp_lt_i32_e32 vcc, v76, v81
	s_nop 1
	v_cndmask_b32_e32 v76, v1, v76, vcc
	v_lshlrev_b32_e32 v76, 2, v76
	ds_bpermute_b32 v78, v76, v77
	s_waitcnt lgkmcnt(0)
	v_add_f32_e32 v78, v77, v78
	v_xor_b32_e32 v77, 2, v1
	v_cmp_lt_i32_e32 vcc, v77, v81
	s_nop 1
	v_cndmask_b32_e32 v77, v1, v77, vcc
	v_lshlrev_b32_e32 v77, 2, v77
	ds_bpermute_b32 v79, v77, v78
	s_waitcnt lgkmcnt(0)
	v_add_f32_e32 v79, v78, v79
	v_xor_b32_e32 v78, 4, v1
	v_cmp_lt_i32_e32 vcc, v78, v81
	s_nop 1
	v_cndmask_b32_e32 v78, v1, v78, vcc
	v_lshlrev_b32_e32 v78, 2, v78
	ds_bpermute_b32 v80, v78, v79
	s_waitcnt lgkmcnt(0)
	v_add_f32_e32 v80, v79, v80
	v_xor_b32_e32 v79, 8, v1
	v_cmp_lt_i32_e32 vcc, v79, v81
	s_nop 1
	v_cndmask_b32_e32 v79, v1, v79, vcc
	v_lshlrev_b32_e32 v79, 2, v79
	ds_bpermute_b32 v106, v79, v80
	s_waitcnt lgkmcnt(0)
	v_add_f32_e32 v106, v80, v106
	v_xor_b32_e32 v80, 16, v1
	v_cmp_lt_i32_e32 vcc, v80, v81
	s_nop 1
	v_cndmask_b32_e32 v80, v1, v80, vcc
	v_lshlrev_b32_e32 v80, 2, v80
	ds_bpermute_b32 v107, v80, v106
	s_waitcnt lgkmcnt(0)
	v_add_f32_e32 v106, v106, v107
	v_xor_b32_e32 v107, 32, v1
	v_cmp_lt_i32_e32 vcc, v107, v81
	s_nop 1
	v_cndmask_b32_e32 v81, v1, v107, vcc
	v_lshlrev_b32_e32 v81, 2, v81
	ds_bpermute_b32 v107, v81, v106
	s_waitcnt lgkmcnt(0)
	v_add_f32_e32 v106, v106, v107
	v_fmamk_f32 v106, v106, 0x3a800000, v67
	v_mul_f32_e32 v107, 0x4b800000, v106
	v_cmp_gt_f32_e32 vcc, s21, v106
	s_nop 1
	v_cndmask_b32_e32 v106, v106, v107, vcc
	v_rsq_f32_e32 v106, v106
	s_nop 0
	v_mul_f32_e32 v107, 0x45800000, v106
	v_cndmask_b32_e32 v106, v106, v107, vcc
	v_pk_mul_f32 v[60:61], v[60:61], v[106:107] op_sel_hi:[1,0]
	v_pk_mul_f32 v[58:59], v[58:59], v[106:107] op_sel_hi:[1,0]
	v_pk_mul_f32 v[64:65], v[64:65], v[106:107] op_sel_hi:[1,0]
	v_pk_mul_f32 v[62:63], v[62:63], v[106:107] op_sel_hi:[1,0]
	s_waitcnt vmcnt(5)
	v_pk_mul_f32 v[58:59], v[82:83], v[58:59]
	v_pk_mul_f32 v[60:61], v[84:85], v[60:61]
	s_waitcnt vmcnt(3)
	v_pk_add_f32 v[82:83], v[92:93], 1.0 op_sel_hi:[1,0]
	v_pk_add_f32 v[84:85], v[90:91], 1.0 op_sel_hi:[1,0]
	v_pk_mul_f32 v[62:63], v[86:87], v[62:63]
	v_pk_mul_f32 v[64:65], v[88:89], v[64:65]
	s_waitcnt vmcnt(2)
	v_pk_add_f32 v[86:87], v[96:97], 1.0 op_sel_hi:[1,0]
	v_pk_add_f32 v[88:89], v[94:95], 1.0 op_sel_hi:[1,0]
	s_waitcnt vmcnt(1)
	v_pk_fma_f32 v[82:83], v[82:83], v[60:61], v[100:101]
	v_pk_fma_f32 v[60:61], v[84:85], v[58:59], v[98:99]
	s_waitcnt vmcnt(0)
; __device__ __forceinline__ unsigned cvt_pk_bf16(float lo, float hi) { unsigned r; asm volatile("v_cvt_pk_bf16_f32 %0, %1, %2" : "=v"(r) : "v"(lo), "v"(hi)); return r; }
; __device__ __forceinline__ void phase0b(const Params& P, int lane, int wave, int bid, int G) {
;     ...
; #pragma unroll
;         for (int rr = 0; rr < 2; ++rr) { const int row = row0 + rr * NGW; if (row >= NTOK) break;
;             const int s = row < NP ? (row >> 12) : 16; const float* md = mod + s * 3072;
;             const float rstd = rsqrtf(wave_sum(ss[rr]) * (1.f / DM) + EPS);
; #pragma unroll
;             for (int jj = 0; jj < 2; ++jj) { const int c = 8 * lane + 512 * jj; f32x4 hv[2];
; #pragma unroll
;                 for (int e = 0; e < 2; ++e) { const f32x4 gn = *(const f32x4*)(P.norm_gain + c + 4 * e), sh = *(const f32x4*)(md + c + 4 * e), scv = *(const f32x4*)(md + 1024 + c + 4 * e);
;                     hv[e] = (v[rr][2 * jj + e] * rstd * gn) * (scv + 1.f) + sh; }
;                 u32x4 o; o.x = cvt_pk_bf16(hv[0].x, hv[0].y); o.y = cvt_pk_bf16(hv[0].z, hv[0].w); o.z = cvt_pk_bf16(hv[1].x, hv[1].y); o.w = cvt_pk_bf16(hv[1].z, hv[1].w);
;                 *(u32x4*)(H + (size_t)row * DM + c) = o; } }
; #pragma unroll
;         for (int rr = 0; rr < 2; ++rr)
; #pragma unroll
;             for (int j = 0; j < 4; ++j) v[rr][j] = vn[rr][j];
	v_pk_fma_f32 v[64:65], v[86:87], v[64:65], v[104:105]
	v_pk_fma_f32 v[62:63], v[88:89], v[62:63], v[102:103]
	v_pk_mul_f32 v[56:57], v[56:57], v[106:107] op_sel_hi:[1,0]
	v_cvt_pk_bf16_f32 v58, v62, v63
	v_cvt_pk_bf16_f32 v59, v64, v65
	v_cvt_pk_bf16_f32 v60, v60, v61
	v_cvt_pk_bf16_f32 v61, v82, v83
	global_store_dwordx4 v[72:73], v[58:61], off
	global_load_dwordx4 v[58:61], v[68:69], off offset:2048
	s_nop 0
	global_load_dwordx4 v[62:65], v74, s[12:13]
	global_load_dwordx4 v[82:85], v[68:69], off offset:2064
	global_load_dwordx4 v[86:89], v74, s[12:13] offset:16
	global_load_dwordx4 v[90:93], v75, s[10:11] offset:2048
	global_load_dwordx4 v[94:97], v75, s[10:11] offset:2064
	v_pk_mul_f32 v[54:55], v[54:55], v[106:107] op_sel_hi:[1,0]
	v_pk_mul_f32 v[52:53], v[52:53], v[106:107] op_sel_hi:[1,0]
	v_pk_mul_f32 v[50:51], v[50:51], v[106:107] op_sel_hi:[1,0]
	s_add_i32 s12, s5, s24
	s_cmp_gt_i32 s12, 0x13fff
	s_waitcnt vmcnt(5)
	v_pk_mul_f32 v[54:55], v[58:59], v[54:55]
	v_pk_mul_f32 v[56:57], v[60:61], v[56:57]
	s_waitcnt vmcnt(4)
	v_pk_add_f32 v[58:59], v[64:65], 1.0 op_sel_hi:[1,0]
	v_pk_add_f32 v[60:61], v[62:63], 1.0 op_sel_hi:[1,0]
	s_waitcnt vmcnt(3)
	v_pk_mul_f32 v[50:51], v[50:51], v[82:83]
	v_pk_mul_f32 v[52:53], v[52:53], v[84:85]
	s_waitcnt vmcnt(2)
	v_pk_add_f32 v[62:63], v[88:89], 1.0 op_sel_hi:[1,0]
	v_pk_add_f32 v[64:65], v[86:87], 1.0 op_sel_hi:[1,0]
	s_waitcnt vmcnt(1)
	v_pk_fma_f32 v[56:57], v[56:57], v[58:59], v[92:93]
	s_waitcnt vmcnt(0)
	v_pk_fma_f32 v[58:59], v[52:53], v[62:63], v[96:97]
	v_pk_fma_f32 v[52:53], v[50:51], v[64:65], v[94:95]
	v_pk_fma_f32 v[54:55], v[54:55], v[60:61], v[90:91]
	s_nop 0
	v_cvt_pk_bf16_f32 v50, v54, v55
	v_cvt_pk_bf16_f32 v51, v56, v57
	v_cvt_pk_bf16_f32 v52, v52, v53
	v_cvt_pk_bf16_f32 v53, v58, v59
	global_store_dwordx4 v[72:73], v[50:53], off offset:1024
	s_cbranch_scc1 .LBB0_93
	s_min_i32 s10, s12, 0x10000
	s_ashr_i32 s10, s10, 12
	s_mulk_i32 s10, 0xc00
	s_ashr_i32 s11, s10, 31
	s_lshl_b64 s[10:11], s[10:11], 2
	s_add_u32 s10, s17, s10
	s_addc_u32 s11, s18, s11
	v_pk_mul_f32 v[50:51], v[48:49], v[48:49]
	v_pk_mul_f32 v[52:53], v[46:47], v[46:47]
	s_add_u32 s14, s10, 0x1000
	v_pk_mov_b32 v[54:55], v[52:53], v[50:51] op_sel:[1,0]
	v_mov_b32_e32 v53, v51
	s_addc_u32 s15, s11, 0
	v_pk_add_f32 v[90:91], v[54:55], v[52:53]
	global_load_dwordx4 v[50:53], v[68:69], off offset:16
	global_load_dwordx4 v[54:57], v[68:69], off
	global_load_dwordx4 v[58:61], v75, s[14:15] offset:16
	global_load_dwordx4 v[62:65], v75, s[14:15]
	global_load_dwordx4 v[82:85], v75, s[10:11] offset:16
	global_load_dwordx4 v[86:89], v75, s[10:11]
	v_pk_mul_f32 v[92:93], v[44:45], v[44:45]
	v_pk_mul_f32 v[94:95], v[42:43], v[42:43]
	v_pk_add_f32 v[90:91], v[90:91], v[90:91] op_sel:[0,1] op_sel_hi:[1,0]
	v_pk_mov_b32 v[96:97], v[94:95], v[92:93] op_sel:[1,0]
	v_mov_b32_e32 v95, v93
	v_pk_add_f32 v[92:93], v[96:97], v[94:95]
	v_mul_f32_e32 v94, v2, v2
	v_mul_f32_e32 v95, v3, v3
	v_pk_add_f32 v[92:93], v[92:93], v[92:93] op_sel:[0,1] op_sel_hi:[1,0]
	v_mov_b32_e32 v91, v94
	v_mov_b32_e32 v93, v95
	v_pk_add_f32 v[90:91], v[90:91], v[92:93]
	v_mul_f32_e32 v92, v7, v7
	v_mul_f32_e32 v94, v9, v9
	v_mul_f32_e32 v96, v4, v4
	v_mul_f32_e32 v97, v5, v5
	v_pk_fma_f32 v[92:93], v[6:7], v[6:7], v[92:93] op_sel_hi:[1,1,0]
	v_pk_fma_f32 v[94:95], v[8:9], v[8:9], v[94:95] op_sel_hi:[1,1,0]
	v_mov_b32_e32 v93, v96
	v_mov_b32_e32 v95, v97
	v_pk_add_f32 v[92:93], v[92:93], v[94:95]
	s_ashr_i32 s13, s12, 31
	v_pk_add_f32 v[90:91], v[90:91], v[92:93]
	s_lshl_b64 s[12:13], s[12:13], 11
	v_add_f32_e32 v90, v90, v91
	ds_bpermute_b32 v76, v76, v90
	s_waitcnt lgkmcnt(0)
	v_add_f32_e32 v76, v90, v76
	ds_bpermute_b32 v77, v77, v76
	s_waitcnt lgkmcnt(0)
	v_add_f32_e32 v76, v76, v77
	ds_bpermute_b32 v77, v78, v76
	s_waitcnt lgkmcnt(0)
	v_add_f32_e32 v76, v76, v77
	ds_bpermute_b32 v77, v79, v76
	s_waitcnt lgkmcnt(0)
	v_add_f32_e32 v76, v76, v77
	ds_bpermute_b32 v77, v80, v76
	s_waitcnt lgkmcnt(0)
	v_add_f32_e32 v76, v76, v77
	ds_bpermute_b32 v77, v81, v76
	s_waitcnt lgkmcnt(0)
	v_add_f32_e32 v76, v76, v77
	v_fmamk_f32 v76, v76, 0x3a800000, v67
	v_mul_f32_e32 v77, 0x4b800000, v76
	v_cmp_gt_f32_e32 vcc, s21, v76
	s_nop 1
	v_cndmask_b32_e32 v76, v76, v77, vcc
	v_rsq_f32_e32 v78, v76
	v_lshl_add_u64 v[76:77], v[70:71], 0, s[12:13]
	v_mul_f32_e32 v79, 0x45800000, v78
	v_cndmask_b32_e32 v78, v78, v79, vcc
	v_pk_mul_f32 v[48:49], v[48:49], v[78:79] op_sel_hi:[1,0]
	v_pk_mul_f32 v[46:47], v[46:47], v[78:79] op_sel_hi:[1,0]
	v_pk_mul_f32 v[44:45], v[44:45], v[78:79] op_sel_hi:[1,0]
	v_pk_mul_f32 v[42:43], v[42:43], v[78:79] op_sel_hi:[1,0]
	s_waitcnt vmcnt(4)
	v_pk_mul_f32 v[46:47], v[54:55], v[46:47]
	v_pk_mul_f32 v[48:49], v[56:57], v[48:49]
	v_pk_mul_f32 v[42:43], v[50:51], v[42:43]
	v_pk_mul_f32 v[44:45], v[52:53], v[44:45]
	s_waitcnt vmcnt(2)
	v_pk_add_f32 v[50:51], v[64:65], 1.0 op_sel_hi:[1,0]
	v_pk_add_f32 v[54:55], v[60:61], 1.0 op_sel_hi:[1,0]
	v_pk_add_f32 v[56:57], v[58:59], 1.0 op_sel_hi:[1,0]
	v_pk_add_f32 v[52:53], v[62:63], 1.0 op_sel_hi:[1,0]
	s_waitcnt vmcnt(0)
	v_pk_fma_f32 v[48:49], v[50:51], v[48:49], v[88:89]
	v_pk_fma_f32 v[50:51], v[54:55], v[44:45], v[84:85]
	v_pk_fma_f32 v[44:45], v[56:57], v[42:43], v[82:83]
	v_pk_fma_f32 v[46:47], v[52:53], v[46:47], v[86:87]
	v_pk_mul_f32 v[8:9], v[8:9], v[78:79] op_sel_hi:[1,0]
	v_cvt_pk_bf16_f32 v42, v46, v47
	v_cvt_pk_bf16_f32 v43, v48, v49
	v_cvt_pk_bf16_f32 v44, v44, v45
	v_cvt_pk_bf16_f32 v45, v50, v51
	global_store_dwordx4 v[76:77], v[42:45], off
	global_load_dwordx4 v[42:45], v[68:69], off offset:2048
	s_nop 0
	global_load_dwordx4 v[46:49], v74, s[14:15]
	global_load_dwordx4 v[50:53], v[68:69], off offset:2064
	global_load_dwordx4 v[54:57], v74, s[14:15] offset:16
	global_load_dwordx4 v[58:61], v75, s[10:11] offset:2048
	global_load_dwordx4 v[62:65], v75, s[10:11] offset:2064
	v_pk_mul_f32 v[6:7], v[6:7], v[78:79] op_sel_hi:[1,0]
	v_pk_mul_f32 v[4:5], v[4:5], v[78:79] op_sel_hi:[1,0]
	v_pk_mul_f32 v[2:3], v[2:3], v[78:79] op_sel_hi:[1,0]
	s_waitcnt vmcnt(5)
	v_pk_mul_f32 v[6:7], v[42:43], v[6:7]
	v_pk_mul_f32 v[8:9], v[44:45], v[8:9]
	s_waitcnt vmcnt(4)
	v_pk_add_f32 v[42:43], v[48:49], 1.0 op_sel_hi:[1,0]
	v_pk_add_f32 v[44:45], v[46:47], 1.0 op_sel_hi:[1,0]
	s_waitcnt vmcnt(3)
	v_pk_mul_f32 v[2:3], v[2:3], v[50:51]
	v_pk_mul_f32 v[4:5], v[4:5], v[52:53]
	s_waitcnt vmcnt(2)
	v_pk_add_f32 v[46:47], v[56:57], 1.0 op_sel_hi:[1,0]
	v_pk_add_f32 v[48:49], v[54:55], 1.0 op_sel_hi:[1,0]
	s_waitcnt vmcnt(1)
	v_pk_fma_f32 v[8:9], v[8:9], v[42:43], v[60:61]
	s_waitcnt vmcnt(0)
	v_pk_fma_f32 v[42:43], v[4:5], v[46:47], v[64:65]
	v_pk_fma_f32 v[4:5], v[2:3], v[48:49], v[62:63]
	v_pk_fma_f32 v[6:7], v[6:7], v[44:45], v[58:59]
	s_nop 0
	v_cvt_pk_bf16_f32 v2, v6, v7
	v_cvt_pk_bf16_f32 v3, v8, v9
	v_cvt_pk_bf16_f32 v4, v4, v5
	v_cvt_pk_bf16_f32 v5, v42, v43
	global_store_dwordx4 v[76:77], v[2:5], off offset:1024
	s_branch .LBB0_93
